# v21 plus: loop-top SALU bookkeeping (gate/up and w_in K-loops) moved behind the first load segment's reads and DMA issue
# baseline (speedup 1.0000x reference)
; #define PG8_STAGE(bufoff, gbase, voff) do { _Pragma("unroll") for (int _i = 0; _i < 2; ++_i) \
;         __builtin_amdgcn_global_load_lds((const unsigned*)((const char*)(gbase) + (voff)[_i]), (LAS unsigned*)(lds + (bufoff) + ldsw + _i * 8192), 16, 0, 0); } while (0)
; #define PG8_LDA(dst, b, h) do { _Pragma("unroll") for (int m = 0; m < 4; ++m) _Pragma("unroll") for (int k = 0; k < 2; ++k) dst[m][k] = *(const LAS bf16x8*)(lds + PG8_SA(b, h) + aoff + m * 2048 + k * 1024); } while (0)
; #define PG8_LDB(dst, b, h) do { _Pragma("unroll") for (int n = 0; n < 2; ++n) _Pragma("unroll") for (int k = 0; k < 2; ++k) dst[n][k] = *(const LAS bf16x8*)(lds + PG8_SB(b, h) + boff + n * 2048 + k * 1024); } while (0)
; #define PG8_MMA(ai, bj, At, Bt) do { __builtin_amdgcn_s_setprio(1); _Pragma("unroll") for (int m = 0; m < 4; ++m) _Pragma("unroll") for (int n = 0; n < 2; ++n) _Pragma("unroll") for (int k = 0; k < 2; ++k) \
;         acc[ai][bj][m][n] = __builtin_amdgcn_mfma_f32_16x16x32_bf16(Bt[n][k], At[m][k], acc[ai][bj][m][n], 0, 0, 0); __builtin_amdgcn_s_setprio(0); } while (0)
; #define PG8_WAIT_V(n) asm volatile("s_waitcnt vmcnt(" #n ")" ::: "memory")
; #define PG8_WAIT_L(n) asm volatile("s_waitcnt lgkmcnt(" #n ")" ::: "memory")
; #define PG8_BAR __builtin_amdgcn_s_barrier()
; template <class Epi, class Sched>
; __device__ __forceinline__ void gemm_phase(LAS unsigned char* lds, const Gemm g, const Sched& S, const Epi& E) {
;     ...
;             const bool last = (t == nt - 2);
;             const char* a1 = cA + (size_t)(t + 1) * kstep;
;             const char* a2 = last ? nA : cA + (size_t)(t + 2) * kstep; const char* b2 = last ? nB : cB + (size_t)(t + 2) * kstep;
;             const char* a3 = a2 + kstep; const char* b3 = b2 + kstep;
;             PG8_LDB(B0, 0, 0); PG8_SCHED; PG8_LDA(At, 0, 0); PG8_STAGE(PG8_SA(1, 1), a1 + hstep, voffA);
;             PG8_WAIT_L(8); PG8_BAR; PG8_WAIT_L(0); PG8_MMA(0, 0, At, B0); PG8_BAR; PG8_SCHED;
;             PG8_LDB(B1, 0, 1); PG8_STAGE(PG8_SB(0, 0), b2, voffB);
;             PG8_BAR; PG8_WAIT_L(0); PG8_MMA(0, 1, At, B1); PG8_BAR;
;             PG8_LDA(At, 0, 1); PG8_STAGE(PG8_SA(0, 0), a2, voffA);
;             PG8_BAR; PG8_WAIT_L(0); PG8_MMA(1, 0, At, B0); PG8_BAR; PG8_SCHED;
;             PG8_STAGE(PG8_SB(0, 1), b2 + hstep, voffB);
;             PG8_WAIT_V(6); PG8_BAR; PG8_MMA(1, 1, At, B1); PG8_BAR;
.LBB0_125:
	ds_read_b128 v[138:141], v129
	ds_read_b128 v[160:163], v129 offset:1024
	ds_read_b128 v[164:167], v129 offset:2048
	ds_read_b128 v[168:171], v129 offset:3072
	s_add_i32 m0, s30, 0xc000
	ds_read_b128 v[172:175], v145
	ds_read_b128 v[200:203], v145 offset:1024
	ds_read_b128 v[204:207], v145 offset:2048
	ds_read_b128 v[208:211], v145 offset:3072
	ds_read_b128 v[212:215], v145 offset:4096
	ds_read_b128 v[216:219], v145 offset:5120
	ds_read_b128 v[220:223], v145 offset:6144
	ds_read_b128 v[224:227], v145 offset:7168
	global_load_lds_dwordx4 v134, s[16:17]
	s_add_i32 m0, s30, 0xe000
	s_nop 0
	global_load_lds_dwordx4 v136, s[16:17]
	s_add_u32 s20, s16, 0xfff80080
	s_addc_u32 s21, s17, -1
	s_add_i32 s45, 0, 0x10000
	s_cmp_eq_u32 s44, 28
	s_cselect_b32 s23, s7, s21
	s_cselect_b32 s22, s40, s20
	s_cselect_b32 s21, s5, s43
	s_cselect_b32 s20, s41, s42
	s_waitcnt lgkmcnt(8)
	s_barrier
	s_waitcnt lgkmcnt(0)
	v_mfma_f32_16x16x32_bf16 v[124:127], v[138:141], v[172:175], v[124:127]
	v_mfma_f32_16x16x32_bf16 v[120:123], v[164:167], v[172:175], v[120:123]
	v_mfma_f32_16x16x32_bf16 v[116:119], v[138:141], v[204:207], v[116:119]
	v_mfma_f32_16x16x32_bf16 v[108:111], v[164:167], v[204:207], v[108:111]
	v_mfma_f32_16x16x32_bf16 v[100:103], v[138:141], v[212:215], v[100:103]
	v_mfma_f32_16x16x32_bf16 v[92:95], v[164:167], v[212:215], v[92:95]
	v_mfma_f32_16x16x32_bf16 v[84:87], v[138:141], v[220:223], v[84:87]
	v_mfma_f32_16x16x32_bf16 v[76:79], v[164:167], v[220:223], v[76:79]
	v_mfma_f32_16x16x32_bf16 v[124:127], v[160:163], v[200:203], v[124:127]
	v_mfma_f32_16x16x32_bf16 v[120:123], v[168:171], v[200:203], v[120:123]
	v_mfma_f32_16x16x32_bf16 v[116:119], v[160:163], v[208:211], v[116:119]
	v_mfma_f32_16x16x32_bf16 v[108:111], v[168:171], v[208:211], v[108:111]
	v_mfma_f32_16x16x32_bf16 v[100:103], v[160:163], v[216:219], v[100:103]
	v_mfma_f32_16x16x32_bf16 v[92:95], v[168:171], v[216:219], v[92:95]
	v_mfma_f32_16x16x32_bf16 v[84:87], v[160:163], v[224:227], v[84:87]
	v_mfma_f32_16x16x32_bf16 v[76:79], v[168:171], v[224:227], v[76:79]
	s_barrier
	s_add_i32 s48, 0, 0x14000
	s_add_i32 s45, s45, s29
	ds_read_b128 v[228:231], v129 offset:16384
	ds_read_b128 v[232:235], v129 offset:17408
	ds_read_b128 v[236:239], v129 offset:18432
	ds_read_b128 v[240:243], v129 offset:19456
	s_add_u32 s84, s20, 0x80
	s_addc_u32 s85, s21, 0
	s_mov_b32 m0, s45
	s_nop 0
	global_load_lds_dwordx4 v148, s[20:21]
	s_add_i32 m0, s45, 0x2000
	s_nop 0
	global_load_lds_dwordx4 v128, s[20:21]
	s_barrier
	s_waitcnt lgkmcnt(0)
	v_mfma_f32_16x16x32_bf16 v[112:115], v[228:231], v[172:175], v[112:115]
	v_mfma_f32_16x16x32_bf16 v[104:107], v[236:239], v[172:175], v[104:107]
	v_mfma_f32_16x16x32_bf16 v[96:99], v[228:231], v[204:207], v[96:99]
	v_mfma_f32_16x16x32_bf16 v[88:91], v[236:239], v[204:207], v[88:91]
	v_mfma_f32_16x16x32_bf16 v[80:83], v[228:231], v[212:215], v[80:83]
	v_mfma_f32_16x16x32_bf16 v[72:75], v[236:239], v[212:215], v[72:75]
	v_mfma_f32_16x16x32_bf16 v[68:71], v[228:231], v[220:223], v[68:71]
	v_mfma_f32_16x16x32_bf16 v[64:67], v[236:239], v[220:223], v[64:67]
	v_mfma_f32_16x16x32_bf16 v[112:115], v[232:235], v[200:203], v[112:115]
	v_mfma_f32_16x16x32_bf16 v[104:107], v[240:243], v[200:203], v[104:107]
	v_mfma_f32_16x16x32_bf16 v[96:99], v[232:235], v[208:211], v[96:99]
	v_mfma_f32_16x16x32_bf16 v[88:91], v[240:243], v[208:211], v[88:91]
	v_mfma_f32_16x16x32_bf16 v[80:83], v[232:235], v[216:219], v[80:83]
	v_mfma_f32_16x16x32_bf16 v[72:75], v[240:243], v[216:219], v[72:75]
	v_mfma_f32_16x16x32_bf16 v[68:71], v[232:235], v[224:227], v[68:71]
	v_mfma_f32_16x16x32_bf16 v[64:67], v[240:243], v[224:227], v[64:67]
	s_barrier
	s_mov_b32 m0, s30
	s_add_u32 s86, s22, 0x80
	s_addc_u32 s87, s23, 0
	ds_read_b128 v[172:175], v145 offset:16384
	ds_read_b128 v[200:203], v145 offset:17408
	ds_read_b128 v[204:207], v145 offset:18432
	ds_read_b128 v[208:211], v145 offset:19456
	ds_read_b128 v[212:215], v145 offset:20480
	ds_read_b128 v[216:219], v145 offset:21504
	ds_read_b128 v[220:223], v145 offset:22528
	ds_read_b128 v[224:227], v145 offset:23552
	global_load_lds_dwordx4 v132, s[22:23]
	s_mov_b32 m0, s31
	s_nop 0
	global_load_lds_dwordx4 v130, s[22:23]
	s_barrier
	s_waitcnt lgkmcnt(0)
	v_mfma_f32_16x16x32_bf16 v[60:63], v[138:141], v[172:175], v[60:63]
	v_mfma_f32_16x16x32_bf16 v[56:59], v[164:167], v[172:175], v[56:59]
	v_mfma_f32_16x16x32_bf16 v[52:55], v[138:141], v[204:207], v[52:55]
	v_mfma_f32_16x16x32_bf16 v[44:47], v[164:167], v[204:207], v[44:47]
	v_mfma_f32_16x16x32_bf16 v[36:39], v[138:141], v[212:215], v[36:39]
	v_mfma_f32_16x16x32_bf16 v[28:31], v[164:167], v[212:215], v[28:31]
	v_mfma_f32_16x16x32_bf16 v[20:23], v[138:141], v[220:223], v[20:23]
	v_mfma_f32_16x16x32_bf16 v[12:15], v[164:167], v[220:223], v[12:15]
	v_mfma_f32_16x16x32_bf16 v[60:63], v[160:163], v[200:203], v[60:63]
	v_mfma_f32_16x16x32_bf16 v[56:59], v[168:171], v[200:203], v[56:59]
	v_mfma_f32_16x16x32_bf16 v[52:55], v[160:163], v[208:211], v[52:55]
	v_mfma_f32_16x16x32_bf16 v[44:47], v[168:171], v[208:211], v[44:47]
	v_mfma_f32_16x16x32_bf16 v[36:39], v[160:163], v[216:219], v[36:39]
	v_mfma_f32_16x16x32_bf16 v[28:31], v[168:171], v[216:219], v[28:31]
	v_mfma_f32_16x16x32_bf16 v[20:23], v[160:163], v[224:227], v[20:23]
	v_mfma_f32_16x16x32_bf16 v[12:15], v[168:171], v[224:227], v[12:15]
	s_barrier
	s_add_u32 s46, s20, 0x80000
	s_addc_u32 s47, s21, 0
	s_add_i32 s45, s48, s29
	s_mov_b32 m0, s45
	s_nop 0
	global_load_lds_dwordx4 v148, s[46:47]
	s_add_i32 m0, s45, 0x2000
	s_nop 0
	global_load_lds_dwordx4 v128, s[46:47]
	s_waitcnt vmcnt(6)
	s_barrier
; #define PG8_STAGE(bufoff, gbase, voff) do { _Pragma("unroll") for (int _i = 0; _i < 2; ++_i) \
;         __builtin_amdgcn_global_load_lds((const unsigned*)((const char*)(gbase) + (voff)[_i]), (LAS unsigned*)(lds + (bufoff) + ldsw + _i * 8192), 16, 0, 0); } while (0)
; #define PG8_LDA(dst, b, h) do { _Pragma("unroll") for (int m = 0; m < 4; ++m) _Pragma("unroll") for (int k = 0; k < 2; ++k) dst[m][k] = *(const LAS bf16x8*)(lds + PG8_SA(b, h) + aoff + m * 2048 + k * 1024); } while (0)
; #define PG8_LDB(dst, b, h) do { _Pragma("unroll") for (int n = 0; n < 2; ++n) _Pragma("unroll") for (int k = 0; k < 2; ++k) dst[n][k] = *(const LAS bf16x8*)(lds + PG8_SB(b, h) + boff + n * 2048 + k * 1024); } while (0)
; #define PG8_MMA(ai, bj, At, Bt) do { __builtin_amdgcn_s_setprio(1); _Pragma("unroll") for (int m = 0; m < 4; ++m) _Pragma("unroll") for (int n = 0; n < 2; ++n) _Pragma("unroll") for (int k = 0; k < 2; ++k) \
;         acc[ai][bj][m][n] = __builtin_amdgcn_mfma_f32_16x16x32_bf16(Bt[n][k], At[m][k], acc[ai][bj][m][n], 0, 0, 0); __builtin_amdgcn_s_setprio(0); } while (0)
; #define PG8_WAIT_V(n) asm volatile("s_waitcnt vmcnt(" #n ")" ::: "memory")
; #define PG8_WAIT_L(n) asm volatile("s_waitcnt lgkmcnt(" #n ")" ::: "memory")
; #define PG8_BAR __builtin_amdgcn_s_barrier()
; #define PG8_SCHED __builtin_amdgcn_sched_barrier(0)
; template <class Epi, class Sched>
; __device__ __forceinline__ void gemm_phase(LAS unsigned char* lds, const Gemm g, const Sched& S, const Epi& E) {
;     ...
;             PG8_WAIT_V(6); PG8_BAR; PG8_MMA(1, 1, At, B1); PG8_BAR;
;             PG8_LDB(B0, 1, 0); PG8_SCHED; PG8_LDA(At, 1, 0); PG8_STAGE(PG8_SA(0, 1), a2 + hstep, voffA);
;             PG8_WAIT_L(8); PG8_BAR; PG8_WAIT_L(0); PG8_MMA(0, 0, At, B0); PG8_BAR; PG8_SCHED;
;             PG8_LDB(B1, 1, 1); PG8_STAGE(PG8_SB(1, 0), b3, voffB);
;             PG8_BAR; PG8_WAIT_L(0); PG8_MMA(0, 1, At, B1); PG8_BAR;
;             PG8_LDA(At, 1, 1); PG8_STAGE(PG8_SA(1, 0), a3, voffA);
;             PG8_BAR; PG8_WAIT_L(0); PG8_MMA(1, 0, At, B0); PG8_BAR; PG8_SCHED;
	v_mfma_f32_16x16x32_bf16 v[48:51], v[228:231], v[172:175], v[48:51]
	v_mfma_f32_16x16x32_bf16 v[40:43], v[236:239], v[172:175], v[40:43]
	v_mfma_f32_16x16x32_bf16 v[32:35], v[228:231], v[204:207], v[32:35]
	v_mfma_f32_16x16x32_bf16 v[24:27], v[236:239], v[204:207], v[24:27]
	v_mfma_f32_16x16x32_bf16 v[16:19], v[228:231], v[212:215], v[16:19]
	v_mfma_f32_16x16x32_bf16 v[8:11], v[236:239], v[212:215], v[8:11]
	v_mfma_f32_16x16x32_bf16 v[4:7], v[228:231], v[220:223], v[4:7]
	v_mfma_f32_16x16x32_bf16 v[0:3], v[236:239], v[220:223], v[0:3]
	v_mfma_f32_16x16x32_bf16 v[48:51], v[232:235], v[200:203], v[48:51]
	v_mfma_f32_16x16x32_bf16 v[40:43], v[240:243], v[200:203], v[40:43]
	v_mfma_f32_16x16x32_bf16 v[32:35], v[232:235], v[208:211], v[32:35]
	v_mfma_f32_16x16x32_bf16 v[24:27], v[240:243], v[208:211], v[24:27]
	v_mfma_f32_16x16x32_bf16 v[16:19], v[232:235], v[216:219], v[16:19]
	v_mfma_f32_16x16x32_bf16 v[8:11], v[240:243], v[216:219], v[8:11]
	v_mfma_f32_16x16x32_bf16 v[4:7], v[232:235], v[224:227], v[4:7]
	v_mfma_f32_16x16x32_bf16 v[0:3], v[240:243], v[224:227], v[0:3]
	s_barrier
	s_add_i32 s45, 0, 0x18000
	ds_read_b128 v[138:141], v129 offset:32768
	ds_read_b128 v[160:163], v129 offset:33792
	ds_read_b128 v[164:167], v129 offset:34816
	ds_read_b128 v[168:171], v129 offset:35840
	s_add_u32 s22, s22, 0x80000
	s_addc_u32 s23, s23, 0
	s_mov_b32 m0, s33
	ds_read_b128 v[172:175], v145 offset:32768
	ds_read_b128 v[200:203], v145 offset:33792
	ds_read_b128 v[204:207], v145 offset:34816
	ds_read_b128 v[208:211], v145 offset:35840
	ds_read_b128 v[212:215], v145 offset:36864
	ds_read_b128 v[216:219], v145 offset:37888
	ds_read_b128 v[220:223], v145 offset:38912
	ds_read_b128 v[224:227], v145 offset:39936
	global_load_lds_dwordx4 v132, s[22:23]
	s_mov_b32 m0, s34
	s_nop 0
	global_load_lds_dwordx4 v130, s[22:23]
	s_waitcnt lgkmcnt(8)
	s_barrier
	s_waitcnt lgkmcnt(0)
	v_mfma_f32_16x16x32_bf16 v[124:127], v[138:141], v[172:175], v[124:127]
	v_mfma_f32_16x16x32_bf16 v[120:123], v[164:167], v[172:175], v[120:123]
	v_mfma_f32_16x16x32_bf16 v[116:119], v[138:141], v[204:207], v[116:119]
	v_mfma_f32_16x16x32_bf16 v[108:111], v[164:167], v[204:207], v[108:111]
	v_mfma_f32_16x16x32_bf16 v[100:103], v[138:141], v[212:215], v[100:103]
	v_mfma_f32_16x16x32_bf16 v[92:95], v[164:167], v[212:215], v[92:95]
	v_mfma_f32_16x16x32_bf16 v[84:87], v[138:141], v[220:223], v[84:87]
	v_mfma_f32_16x16x32_bf16 v[76:79], v[164:167], v[220:223], v[76:79]
	v_mfma_f32_16x16x32_bf16 v[124:127], v[160:163], v[200:203], v[124:127]
	v_mfma_f32_16x16x32_bf16 v[120:123], v[168:171], v[200:203], v[120:123]
	v_mfma_f32_16x16x32_bf16 v[116:119], v[160:163], v[208:211], v[116:119]
	v_mfma_f32_16x16x32_bf16 v[108:111], v[168:171], v[208:211], v[108:111]
	v_mfma_f32_16x16x32_bf16 v[100:103], v[160:163], v[216:219], v[100:103]
	v_mfma_f32_16x16x32_bf16 v[92:95], v[168:171], v[216:219], v[92:95]
	v_mfma_f32_16x16x32_bf16 v[84:87], v[160:163], v[224:227], v[84:87]
	v_mfma_f32_16x16x32_bf16 v[76:79], v[168:171], v[224:227], v[76:79]
	s_barrier
	s_add_i32 s22, 0, 0x1c000
	s_add_i32 s23, s45, s29
	s_mov_b32 m0, s23
	ds_read_b128 v[228:231], v129 offset:49152
	ds_read_b128 v[232:235], v129 offset:50176
	ds_read_b128 v[236:239], v129 offset:51200
	ds_read_b128 v[240:243], v129 offset:52224
	global_load_lds_dwordx4 v148, s[84:85]
	s_add_i32 m0, s23, 0x2000
	s_nop 0
	global_load_lds_dwordx4 v128, s[84:85]
	s_barrier
	s_waitcnt lgkmcnt(0)
	v_mfma_f32_16x16x32_bf16 v[112:115], v[228:231], v[172:175], v[112:115]
	v_mfma_f32_16x16x32_bf16 v[104:107], v[236:239], v[172:175], v[104:107]
	v_mfma_f32_16x16x32_bf16 v[96:99], v[228:231], v[204:207], v[96:99]
	v_mfma_f32_16x16x32_bf16 v[88:91], v[236:239], v[204:207], v[88:91]
	v_mfma_f32_16x16x32_bf16 v[80:83], v[228:231], v[212:215], v[80:83]
	v_mfma_f32_16x16x32_bf16 v[72:75], v[236:239], v[212:215], v[72:75]
	v_mfma_f32_16x16x32_bf16 v[68:71], v[228:231], v[220:223], v[68:71]
	v_mfma_f32_16x16x32_bf16 v[64:67], v[236:239], v[220:223], v[64:67]
	v_mfma_f32_16x16x32_bf16 v[112:115], v[232:235], v[200:203], v[112:115]
	v_mfma_f32_16x16x32_bf16 v[104:107], v[240:243], v[200:203], v[104:107]
	v_mfma_f32_16x16x32_bf16 v[96:99], v[232:235], v[208:211], v[96:99]
	v_mfma_f32_16x16x32_bf16 v[88:91], v[240:243], v[208:211], v[88:91]
	v_mfma_f32_16x16x32_bf16 v[80:83], v[232:235], v[216:219], v[80:83]
	v_mfma_f32_16x16x32_bf16 v[72:75], v[240:243], v[216:219], v[72:75]
	v_mfma_f32_16x16x32_bf16 v[68:71], v[232:235], v[224:227], v[68:71]
	v_mfma_f32_16x16x32_bf16 v[64:67], v[240:243], v[224:227], v[64:67]
	s_barrier
	s_mov_b32 m0, s35
	ds_read_b128 v[172:175], v145 offset:49152
	ds_read_b128 v[200:203], v145 offset:50176
	ds_read_b128 v[204:207], v145 offset:51200
	ds_read_b128 v[208:211], v145 offset:52224
	ds_read_b128 v[212:215], v145 offset:53248
	ds_read_b128 v[216:219], v145 offset:54272
	ds_read_b128 v[220:223], v145 offset:55296
	ds_read_b128 v[224:227], v145 offset:56320
	global_load_lds_dwordx4 v132, s[86:87]
	s_mov_b32 m0, s36
	s_nop 0
	global_load_lds_dwordx4 v130, s[86:87]
	s_barrier
	s_waitcnt lgkmcnt(0)
	v_mfma_f32_16x16x32_bf16 v[60:63], v[138:141], v[172:175], v[60:63]
	v_mfma_f32_16x16x32_bf16 v[56:59], v[164:167], v[172:175], v[56:59]
	v_mfma_f32_16x16x32_bf16 v[52:55], v[138:141], v[204:207], v[52:55]
	v_mfma_f32_16x16x32_bf16 v[44:47], v[164:167], v[204:207], v[44:47]
	v_mfma_f32_16x16x32_bf16 v[36:39], v[138:141], v[212:215], v[36:39]
	v_mfma_f32_16x16x32_bf16 v[28:31], v[164:167], v[212:215], v[28:31]
	v_mfma_f32_16x16x32_bf16 v[20:23], v[138:141], v[220:223], v[20:23]
	v_mfma_f32_16x16x32_bf16 v[12:15], v[164:167], v[220:223], v[12:15]
	v_mfma_f32_16x16x32_bf16 v[60:63], v[160:163], v[200:203], v[60:63]
	v_mfma_f32_16x16x32_bf16 v[56:59], v[168:171], v[200:203], v[56:59]
	v_mfma_f32_16x16x32_bf16 v[52:55], v[160:163], v[208:211], v[52:55]
	v_mfma_f32_16x16x32_bf16 v[44:47], v[168:171], v[208:211], v[44:47]
	v_mfma_f32_16x16x32_bf16 v[36:39], v[160:163], v[216:219], v[36:39]
	v_mfma_f32_16x16x32_bf16 v[28:31], v[168:171], v[216:219], v[28:31]
	v_mfma_f32_16x16x32_bf16 v[20:23], v[160:163], v[224:227], v[20:23]
	v_mfma_f32_16x16x32_bf16 v[12:15], v[168:171], v[224:227], v[12:15]
	s_barrier
; __device__ __forceinline__ unsigned cvt_pk_bf16(float lo, float hi) { unsigned r; asm("v_cvt_pk_bf16_f32 %0, %1, %2" : "=v"(r) : "v"(lo), "v"(hi)); return r; }
; #define PG8_STAGE(bufoff, gbase, voff) do { _Pragma("unroll") for (int _i = 0; _i < 2; ++_i) \
;         __builtin_amdgcn_global_load_lds((const unsigned*)((const char*)(gbase) + (voff)[_i]), (LAS unsigned*)(lds + (bufoff) + ldsw + _i * 8192), 16, 0, 0); } while (0)
; #define PG8_MMA(ai, bj, At, Bt) do { __builtin_amdgcn_s_setprio(1); _Pragma("unroll") for (int m = 0; m < 4; ++m) _Pragma("unroll") for (int n = 0; n < 2; ++n) _Pragma("unroll") for (int k = 0; k < 2; ++k) \
;         acc[ai][bj][m][n] = __builtin_amdgcn_mfma_f32_16x16x32_bf16(Bt[n][k], At[m][k], acc[ai][bj][m][n], 0, 0, 0); __builtin_amdgcn_s_setprio(0); } while (0)
; #define PG8_WAIT_V(n) asm volatile("s_waitcnt vmcnt(" #n ")" ::: "memory")
; #define PG8_BAR __builtin_amdgcn_s_barrier()
;     __device__ __forceinline__ void operator()(const f32x4 (&acc)[2][2][4][2], const Unit& u, int wr, int wc, int fr, int fq) const {
;         const int row0 = u.pm * BM + wr * 64 + fr, col0 = u.pn * BM + wc * 32 + 8 * fq;
; #pragma unroll
;         for (int ai = 0; ai < 2; ++ai)
; #pragma unroll
;             for (int m = 0; m < 4; ++m) { bf16_t* rowp = O + (size_t)(row0 + ai * HALF + m * 16) * ldc + col0;
; #pragma unroll
;                 for (int bj = 0; bj < 2; ++bj) { const f32x4 v0 = acc[ai][bj][m][0], v1 = acc[ai][bj][m][1];
;                     u32x4 w; w.x = cvt_pk_bf16(v0[0], v0[1]); w.y = cvt_pk_bf16(v0[2], v0[3]); w.z = cvt_pk_bf16(v1[0], v1[1]); w.w = cvt_pk_bf16(v1[2], v1[3]);
;                     *(u32x4*)(rowp + bj * HALF) = w; } }
; template <class Epi, class Sched>
; __device__ __forceinline__ void gemm_phase(LAS unsigned char* lds, const Gemm g, const Sched& S, const Epi& E) {
;     ...
;             PG8_STAGE(PG8_SB(1, 1), b3 + hstep, voffB);
;             PG8_WAIT_V(6); PG8_BAR; PG8_MMA(1, 1, At, B1); PG8_BAR;
	s_add_u32 s20, s20, 0x80080
	s_addc_u32 s21, s21, 0
	s_add_i32 s22, s22, s29
	s_mov_b32 m0, s22
	s_nop 0
	global_load_lds_dwordx4 v148, s[20:21]
	s_add_i32 m0, s22, 0x2000
	s_nop 0
	global_load_lds_dwordx4 v128, s[20:21]
	s_add_i32 s44, s44, 2
	s_add_u32 s16, s16, 0x100
	s_addc_u32 s17, s17, 0
	s_add_u32 s42, s42, 0x100
	s_addc_u32 s43, s43, 0
	s_cmp_gt_u32 s44, 29
	s_waitcnt vmcnt(6)
	s_barrier
	v_mfma_f32_16x16x32_bf16 v[48:51], v[228:231], v[172:175], v[48:51]
	v_mfma_f32_16x16x32_bf16 v[40:43], v[236:239], v[172:175], v[40:43]
	v_mfma_f32_16x16x32_bf16 v[32:35], v[228:231], v[204:207], v[32:35]
	v_mfma_f32_16x16x32_bf16 v[24:27], v[236:239], v[204:207], v[24:27]
	v_mfma_f32_16x16x32_bf16 v[16:19], v[228:231], v[212:215], v[16:19]
	v_mfma_f32_16x16x32_bf16 v[8:11], v[236:239], v[212:215], v[8:11]
	v_mfma_f32_16x16x32_bf16 v[4:7], v[228:231], v[220:223], v[4:7]
	v_mfma_f32_16x16x32_bf16 v[0:3], v[236:239], v[220:223], v[0:3]
	v_mfma_f32_16x16x32_bf16 v[48:51], v[232:235], v[200:203], v[48:51]
	v_mfma_f32_16x16x32_bf16 v[40:43], v[240:243], v[200:203], v[40:43]
	v_mfma_f32_16x16x32_bf16 v[32:35], v[232:235], v[208:211], v[32:35]
	v_mfma_f32_16x16x32_bf16 v[24:27], v[240:243], v[208:211], v[24:27]
	v_mfma_f32_16x16x32_bf16 v[16:19], v[232:235], v[216:219], v[16:19]
	v_mfma_f32_16x16x32_bf16 v[8:11], v[240:243], v[216:219], v[8:11]
	v_mfma_f32_16x16x32_bf16 v[4:7], v[232:235], v[224:227], v[4:7]
	v_mfma_f32_16x16x32_bf16 v[0:3], v[240:243], v[224:227], v[0:3]
	s_barrier
	s_cbranch_scc0 .LBB0_125
	v_lshl_add_u32 v160, s39, 8, v142
	v_lshl_or_b32 v140, s38, 8, v144
	v_ashrrev_i32_e32 v141, 31, v140
	v_mov_b64_e32 v[138:139], s[2:3]
	v_cvt_pk_bf16_f32 v68, v68, v69
	v_cvt_pk_bf16_f32 v69, v70, v71
	v_cvt_pk_bf16_f32 v70, v64, v65
	v_add_u32_e32 v64, 0x80, v160
	v_mad_i64_i32 v[146:147], s[16:17], v160, s56, v[138:139]
	v_lshlrev_b64 v[140:141], 1, v[140:141]
	v_cvt_pk_bf16_f32 v112, v112, v113
	v_cvt_pk_bf16_f32 v113, v114, v115
	v_cvt_pk_bf16_f32 v114, v104, v105
	v_or_b32_e32 v104, 16, v160
	v_mad_i64_i32 v[64:65], s[16:17], v64, s56, v[138:139]
	v_cvt_pk_bf16_f32 v48, v48, v49
	v_cvt_pk_bf16_f32 v49, v50, v51
	v_cvt_pk_bf16_f32 v50, v40, v41
	v_add_u32_e32 v40, 0x90, v160
	v_lshl_add_u64 v[146:147], v[146:147], 0, v[140:141]
	v_mad_i64_i32 v[104:105], s[16:17], v104, s56, v[138:139]
	v_cvt_pk_bf16_f32 v96, v96, v97
	v_cvt_pk_bf16_f32 v97, v98, v99
	v_cvt_pk_bf16_f32 v98, v88, v89
	v_or_b32_e32 v88, 32, v160
	v_lshl_add_u64 v[64:65], v[64:65], 0, v[140:141]
	v_mad_i64_i32 v[40:41], s[16:17], v40, s56, v[138:139]
	v_cvt_pk_bf16_f32 v32, v32, v33
	v_cvt_pk_bf16_f32 v33, v34, v35
	v_cvt_pk_bf16_f32 v34, v24, v25
	v_add_u32_e32 v24, 0xa0, v160
	v_cvt_pk_bf16_f32 v115, v106, v107
	global_store_dwordx4 v[146:147], v[112:115], off offset:256
	v_mad_i64_i32 v[88:89], s[16:17], v88, s56, v[138:139]
	s_nop 0
	v_lshl_add_u64 v[112:113], v[104:105], 0, v[140:141]
	v_cvt_pk_bf16_f32 v80, v80, v81
	v_cvt_pk_bf16_f32 v81, v82, v83
	v_cvt_pk_bf16_f32 v82, v72, v73
	v_or_b32_e32 v72, 48, v160
	v_cvt_pk_bf16_f32 v51, v42, v43
	global_store_dwordx4 v[64:65], v[48:51], off offset:256
	v_mad_i64_i32 v[24:25], s[16:17], v24, s56, v[138:139]
	s_nop 0
	v_lshl_add_u64 v[48:49], v[40:41], 0, v[140:141]
	v_cvt_pk_bf16_f32 v16, v16, v17
	v_cvt_pk_bf16_f32 v17, v18, v19
	v_cvt_pk_bf16_f32 v18, v8, v9
	v_add_u32_e32 v8, 0xb0, v160
	v_cvt_pk_bf16_f32 v99, v90, v91
	global_store_dwordx4 v[112:113], v[96:99], off offset:256
	v_mad_i64_i32 v[72:73], s[16:17], v72, s56, v[138:139]
	s_nop 0
	v_lshl_add_u64 v[96:97], v[88:89], 0, v[140:141]
	v_cvt_pk_bf16_f32 v35, v26, v27
	global_store_dwordx4 v[48:49], v[32:35], off offset:256
	v_mad_i64_i32 v[8:9], s[16:17], v8, s56, v[138:139]
	s_nop 0
	v_lshl_add_u64 v[32:33], v[24:25], 0, v[140:141]
	v_cvt_pk_bf16_f32 v83, v74, v75
	global_store_dwordx4 v[96:97], v[80:83], off offset:256
	v_cvt_pk_bf16_f32 v19, v10, v11
	global_store_dwordx4 v[32:33], v[16:19], off offset:256
	s_and_b64 vcc, exec, s[0:1]
	v_lshl_add_u64 v[80:81], v[72:73], 0, v[140:141]
	v_lshl_add_u64 v[16:17], v[8:9], 0, v[140:141]
	s_mov_b32 s38, s4
	s_mov_b32 s39, s6
	s_mov_b64 s[20:21], s[14:15]
	s_mov_b64 s[16:17], s[12:13]
	v_cvt_pk_bf16_f32 v124, v124, v125
	v_cvt_pk_bf16_f32 v125, v126, v127
	v_cvt_pk_bf16_f32 v126, v120, v121
	v_cvt_pk_bf16_f32 v127, v122, v123
	global_store_dwordx4 v[146:147], v[124:127], off
	v_cvt_pk_bf16_f32 v104, v116, v117
	v_cvt_pk_bf16_f32 v105, v118, v119
	v_cvt_pk_bf16_f32 v106, v108, v109
	v_cvt_pk_bf16_f32 v107, v110, v111
	global_store_dwordx4 v[112:113], v[104:107], off
	v_cvt_pk_bf16_f32 v88, v100, v101
	v_cvt_pk_bf16_f32 v89, v102, v103
	v_cvt_pk_bf16_f32 v90, v92, v93
	v_cvt_pk_bf16_f32 v91, v94, v95
	global_store_dwordx4 v[96:97], v[88:91], off
	v_cvt_pk_bf16_f32 v72, v84, v85
	v_cvt_pk_bf16_f32 v73, v86, v87
	v_cvt_pk_bf16_f32 v74, v76, v77
	v_cvt_pk_bf16_f32 v75, v78, v79
	global_store_dwordx4 v[80:81], v[72:75], off
	v_cvt_pk_bf16_f32 v71, v66, v67
	global_store_dwordx4 v[80:81], v[68:71], off offset:256
	v_cvt_pk_bf16_f32 v60, v60, v61
	v_cvt_pk_bf16_f32 v61, v62, v63
	v_cvt_pk_bf16_f32 v62, v56, v57
	v_cvt_pk_bf16_f32 v63, v58, v59
	global_store_dwordx4 v[64:65], v[60:63], off
	v_cvt_pk_bf16_f32 v40, v52, v53
	v_cvt_pk_bf16_f32 v41, v54, v55
	v_cvt_pk_bf16_f32 v42, v44, v45
	v_cvt_pk_bf16_f32 v43, v46, v47
	global_store_dwordx4 v[48:49], v[40:43], off
	v_cvt_pk_bf16_f32 v24, v36, v37
	v_cvt_pk_bf16_f32 v25, v38, v39
	v_cvt_pk_bf16_f32 v26, v28, v29
	v_cvt_pk_bf16_f32 v27, v30, v31
	global_store_dwordx4 v[32:33], v[24:27], off
	v_cvt_pk_bf16_f32 v8, v20, v21
	v_cvt_pk_bf16_f32 v9, v22, v23
	v_cvt_pk_bf16_f32 v10, v12, v13
	v_cvt_pk_bf16_f32 v11, v14, v15
	global_store_dwordx4 v[16:17], v[8:11], off
	v_cvt_pk_bf16_f32 v4, v4, v5
	v_cvt_pk_bf16_f32 v5, v6, v7
	v_cvt_pk_bf16_f32 v6, v0, v1
	v_cvt_pk_bf16_f32 v7, v2, v3
	global_store_dwordx4 v[16:17], v[4:7], off offset:256
	s_cbranch_vccz .LBB0_118
	s_waitcnt vmcnt(0)
	s_cmpk_gt_u32 s24, 0xff
	s_cbranch_scc1 .LBB0_129
	s_barrier

; #define PG8_STAGE(bufoff, gbase, voff) do { _Pragma("unroll") for (int _i = 0; _i < 2; ++_i) \
;         __builtin_amdgcn_global_load_lds((const unsigned*)((const char*)(gbase) + (voff)[_i]), (LAS unsigned*)(lds + (bufoff) + ldsw + _i * 8192), 16, 0, 0); } while (0)
; #define PG8_LDA(dst, b, h) do { _Pragma("unroll") for (int m = 0; m < 4; ++m) _Pragma("unroll") for (int k = 0; k < 2; ++k) dst[m][k] = *(const LAS bf16x8*)(lds + PG8_SA(b, h) + aoff + m * 2048 + k * 1024); } while (0)
; #define PG8_LDB(dst, b, h) do { _Pragma("unroll") for (int n = 0; n < 2; ++n) _Pragma("unroll") for (int k = 0; k < 2; ++k) dst[n][k] = *(const LAS bf16x8*)(lds + PG8_SB(b, h) + boff + n * 2048 + k * 1024); } while (0)
; #define PG8_MMA(ai, bj, At, Bt) do { __builtin_amdgcn_s_setprio(1); _Pragma("unroll") for (int m = 0; m < 4; ++m) _Pragma("unroll") for (int n = 0; n < 2; ++n) _Pragma("unroll") for (int k = 0; k < 2; ++k) \
;         acc[ai][bj][m][n] = __builtin_amdgcn_mfma_f32_16x16x32_bf16(Bt[n][k], At[m][k], acc[ai][bj][m][n], 0, 0, 0); __builtin_amdgcn_s_setprio(0); } while (0)
; #define PG8_WAIT_V(n) asm volatile("s_waitcnt vmcnt(" #n ")" ::: "memory")
; #define PG8_WAIT_L(n) asm volatile("s_waitcnt lgkmcnt(" #n ")" ::: "memory")
; #define PG8_BAR __builtin_amdgcn_s_barrier()
; template <class Epi, class Sched>
; __device__ __forceinline__ void gemm_phase(LAS unsigned char* lds, const Gemm g, const Sched& S, const Epi& E) {
;     ...
;             const bool last = (t == nt - 2);
;             const char* a1 = cA + (size_t)(t + 1) * kstep;
;             const char* a2 = last ? nA : cA + (size_t)(t + 2) * kstep; const char* b2 = last ? nB : cB + (size_t)(t + 2) * kstep;
;             const char* a3 = a2 + kstep; const char* b3 = b2 + kstep;
;             PG8_LDB(B0, 0, 0); PG8_SCHED; PG8_LDA(At, 0, 0); PG8_STAGE(PG8_SA(1, 1), a1 + hstep, voffA);
;             PG8_WAIT_L(8); PG8_BAR; PG8_WAIT_L(0); PG8_MMA(0, 0, At, B0); PG8_BAR; PG8_SCHED;
;             PG8_LDB(B1, 0, 1); PG8_STAGE(PG8_SB(0, 0), b2, voffB);
;             PG8_BAR; PG8_WAIT_L(0); PG8_MMA(0, 1, At, B1); PG8_BAR;
;             PG8_LDA(At, 0, 1); PG8_STAGE(PG8_SA(0, 0), a2, voffA);
;             PG8_BAR; PG8_WAIT_L(0); PG8_MMA(1, 0, At, B0); PG8_BAR; PG8_SCHED;
;             PG8_STAGE(PG8_SB(0, 1), b2 + hstep, voffB);
;             PG8_WAIT_V(6); PG8_BAR; PG8_MMA(1, 1, At, B1); PG8_BAR;
.LBB0_213:
	ds_read_b128 v[144:147], v129
	ds_read_b128 v[160:163], v129 offset:1024
	ds_read_b128 v[164:167], v129 offset:2048
	ds_read_b128 v[168:171], v129 offset:3072
	s_add_i32 m0, s30, 0xc000
	ds_read_b128 v[172:175], v143
	ds_read_b128 v[200:203], v143 offset:1024
	ds_read_b128 v[204:207], v143 offset:2048
	ds_read_b128 v[208:211], v143 offset:3072
	ds_read_b128 v[212:215], v143 offset:4096
	ds_read_b128 v[216:219], v143 offset:5120
	ds_read_b128 v[220:223], v143 offset:6144
	ds_read_b128 v[224:227], v143 offset:7168
	global_load_lds_dwordx4 v134, s[16:17]
	s_add_i32 m0, s30, 0xe000
	s_nop 0
	global_load_lds_dwordx4 v136, s[16:17]
	s_add_u32 s20, s16, 0xfff80080
	s_addc_u32 s21, s17, -1
	s_add_i32 s45, 0, 0x10000
	s_cmp_eq_u32 s44, 28
	s_cselect_b32 s23, s11, s21
	s_cselect_b32 s22, s40, s20
	s_cselect_b32 s21, s7, s43
	s_cselect_b32 s20, s41, s42
	s_waitcnt lgkmcnt(8)
	s_barrier
	s_waitcnt lgkmcnt(0)
	v_mfma_f32_16x16x32_bf16 v[124:127], v[144:147], v[172:175], v[124:127]
	v_mfma_f32_16x16x32_bf16 v[116:119], v[164:167], v[172:175], v[116:119]
	v_mfma_f32_16x16x32_bf16 v[108:111], v[144:147], v[204:207], v[108:111]
	v_mfma_f32_16x16x32_bf16 v[100:103], v[164:167], v[204:207], v[100:103]
	v_mfma_f32_16x16x32_bf16 v[92:95], v[144:147], v[212:215], v[92:95]
	v_mfma_f32_16x16x32_bf16 v[84:87], v[164:167], v[212:215], v[84:87]
	v_mfma_f32_16x16x32_bf16 v[76:79], v[144:147], v[220:223], v[76:79]
	v_mfma_f32_16x16x32_bf16 v[68:71], v[164:167], v[220:223], v[68:71]
	v_mfma_f32_16x16x32_bf16 v[124:127], v[160:163], v[200:203], v[124:127]
	v_mfma_f32_16x16x32_bf16 v[116:119], v[168:171], v[200:203], v[116:119]
	v_mfma_f32_16x16x32_bf16 v[108:111], v[160:163], v[208:211], v[108:111]
	v_mfma_f32_16x16x32_bf16 v[100:103], v[168:171], v[208:211], v[100:103]
	v_mfma_f32_16x16x32_bf16 v[92:95], v[160:163], v[216:219], v[92:95]
	v_mfma_f32_16x16x32_bf16 v[84:87], v[168:171], v[216:219], v[84:87]
	v_mfma_f32_16x16x32_bf16 v[76:79], v[160:163], v[224:227], v[76:79]
	v_mfma_f32_16x16x32_bf16 v[68:71], v[168:171], v[224:227], v[68:71]
	s_barrier
	s_add_i32 s48, 0, 0x14000
	s_add_i32 s45, s45, s29
	ds_read_b128 v[228:231], v129 offset:16384
	ds_read_b128 v[232:235], v129 offset:17408
	ds_read_b128 v[236:239], v129 offset:18432
	ds_read_b128 v[240:243], v129 offset:19456
	s_add_u32 s84, s20, 0x80
	s_addc_u32 s85, s21, 0
	s_mov_b32 m0, s45
	s_nop 0
	global_load_lds_dwordx4 v148, s[20:21]
	s_add_i32 m0, s45, 0x2000
	s_nop 0
	global_load_lds_dwordx4 v128, s[20:21]
	s_barrier
	s_waitcnt lgkmcnt(0)
	v_mfma_f32_16x16x32_bf16 v[120:123], v[228:231], v[172:175], v[120:123]
	v_mfma_f32_16x16x32_bf16 v[112:115], v[236:239], v[172:175], v[112:115]
	v_mfma_f32_16x16x32_bf16 v[104:107], v[228:231], v[204:207], v[104:107]
	v_mfma_f32_16x16x32_bf16 v[96:99], v[236:239], v[204:207], v[96:99]
	v_mfma_f32_16x16x32_bf16 v[88:91], v[228:231], v[212:215], v[88:91]
	v_mfma_f32_16x16x32_bf16 v[80:83], v[236:239], v[212:215], v[80:83]
	v_mfma_f32_16x16x32_bf16 v[72:75], v[228:231], v[220:223], v[72:75]
	v_mfma_f32_16x16x32_bf16 v[64:67], v[236:239], v[220:223], v[64:67]
	v_mfma_f32_16x16x32_bf16 v[120:123], v[232:235], v[200:203], v[120:123]
	v_mfma_f32_16x16x32_bf16 v[112:115], v[240:243], v[200:203], v[112:115]
	v_mfma_f32_16x16x32_bf16 v[104:107], v[232:235], v[208:211], v[104:107]
	v_mfma_f32_16x16x32_bf16 v[96:99], v[240:243], v[208:211], v[96:99]
	v_mfma_f32_16x16x32_bf16 v[88:91], v[232:235], v[216:219], v[88:91]
	v_mfma_f32_16x16x32_bf16 v[80:83], v[240:243], v[216:219], v[80:83]
	v_mfma_f32_16x16x32_bf16 v[72:75], v[232:235], v[224:227], v[72:75]
	v_mfma_f32_16x16x32_bf16 v[64:67], v[240:243], v[224:227], v[64:67]
	s_barrier
	s_mov_b32 m0, s30
	s_add_u32 s86, s22, 0x80
	s_addc_u32 s87, s23, 0
	ds_read_b128 v[172:175], v143 offset:16384
	ds_read_b128 v[200:203], v143 offset:17408
	ds_read_b128 v[204:207], v143 offset:18432
	ds_read_b128 v[208:211], v143 offset:19456
	ds_read_b128 v[212:215], v143 offset:20480
	ds_read_b128 v[216:219], v143 offset:21504
	ds_read_b128 v[220:223], v143 offset:22528
	ds_read_b128 v[224:227], v143 offset:23552
	global_load_lds_dwordx4 v132, s[22:23]
	s_mov_b32 m0, s31
	s_nop 0
	global_load_lds_dwordx4 v130, s[22:23]
	s_barrier
	s_waitcnt lgkmcnt(0)
	v_mfma_f32_16x16x32_bf16 v[60:63], v[144:147], v[172:175], v[60:63]
	v_mfma_f32_16x16x32_bf16 v[52:55], v[164:167], v[172:175], v[52:55]
	v_mfma_f32_16x16x32_bf16 v[44:47], v[144:147], v[204:207], v[44:47]
	v_mfma_f32_16x16x32_bf16 v[36:39], v[164:167], v[204:207], v[36:39]
	v_mfma_f32_16x16x32_bf16 v[28:31], v[144:147], v[212:215], v[28:31]
	v_mfma_f32_16x16x32_bf16 v[20:23], v[164:167], v[212:215], v[20:23]
	v_mfma_f32_16x16x32_bf16 v[12:15], v[144:147], v[220:223], v[12:15]
	v_mfma_f32_16x16x32_bf16 v[4:7], v[164:167], v[220:223], v[4:7]
	v_mfma_f32_16x16x32_bf16 v[60:63], v[160:163], v[200:203], v[60:63]
	v_mfma_f32_16x16x32_bf16 v[52:55], v[168:171], v[200:203], v[52:55]
	v_mfma_f32_16x16x32_bf16 v[44:47], v[160:163], v[208:211], v[44:47]
	v_mfma_f32_16x16x32_bf16 v[36:39], v[168:171], v[208:211], v[36:39]
	v_mfma_f32_16x16x32_bf16 v[28:31], v[160:163], v[216:219], v[28:31]
	v_mfma_f32_16x16x32_bf16 v[20:23], v[168:171], v[216:219], v[20:23]
	v_mfma_f32_16x16x32_bf16 v[12:15], v[160:163], v[224:227], v[12:15]
	v_mfma_f32_16x16x32_bf16 v[4:7], v[168:171], v[224:227], v[4:7]
	s_barrier
	s_add_u32 s46, s20, 0x80000
	s_addc_u32 s47, s21, 0
	s_add_i32 s45, s48, s29
	s_mov_b32 m0, s45
	s_nop 0
	global_load_lds_dwordx4 v148, s[46:47]
	s_add_i32 m0, s45, 0x2000
	s_nop 0
	global_load_lds_dwordx4 v128, s[46:47]
	s_waitcnt vmcnt(6)
	s_barrier
; #define PG8_STAGE(bufoff, gbase, voff) do { _Pragma("unroll") for (int _i = 0; _i < 2; ++_i) \
;         __builtin_amdgcn_global_load_lds((const unsigned*)((const char*)(gbase) + (voff)[_i]), (LAS unsigned*)(lds + (bufoff) + ldsw + _i * 8192), 16, 0, 0); } while (0)
; #define PG8_LDA(dst, b, h) do { _Pragma("unroll") for (int m = 0; m < 4; ++m) _Pragma("unroll") for (int k = 0; k < 2; ++k) dst[m][k] = *(const LAS bf16x8*)(lds + PG8_SA(b, h) + aoff + m * 2048 + k * 1024); } while (0)
; #define PG8_LDB(dst, b, h) do { _Pragma("unroll") for (int n = 0; n < 2; ++n) _Pragma("unroll") for (int k = 0; k < 2; ++k) dst[n][k] = *(const LAS bf16x8*)(lds + PG8_SB(b, h) + boff + n * 2048 + k * 1024); } while (0)
; #define PG8_MMA(ai, bj, At, Bt) do { __builtin_amdgcn_s_setprio(1); _Pragma("unroll") for (int m = 0; m < 4; ++m) _Pragma("unroll") for (int n = 0; n < 2; ++n) _Pragma("unroll") for (int k = 0; k < 2; ++k) \
;         acc[ai][bj][m][n] = __builtin_amdgcn_mfma_f32_16x16x32_bf16(Bt[n][k], At[m][k], acc[ai][bj][m][n], 0, 0, 0); __builtin_amdgcn_s_setprio(0); } while (0)
; #define PG8_WAIT_V(n) asm volatile("s_waitcnt vmcnt(" #n ")" ::: "memory")
; #define PG8_WAIT_L(n) asm volatile("s_waitcnt lgkmcnt(" #n ")" ::: "memory")
; #define PG8_BAR __builtin_amdgcn_s_barrier()
; #define PG8_SCHED __builtin_amdgcn_sched_barrier(0)
; template <class Epi, class Sched>
; __device__ __forceinline__ void gemm_phase(LAS unsigned char* lds, const Gemm g, const Sched& S, const Epi& E) {
;     ...
;             PG8_WAIT_V(6); PG8_BAR; PG8_MMA(1, 1, At, B1); PG8_BAR;
;             PG8_LDB(B0, 1, 0); PG8_SCHED; PG8_LDA(At, 1, 0); PG8_STAGE(PG8_SA(0, 1), a2 + hstep, voffA);
;             PG8_WAIT_L(8); PG8_BAR; PG8_WAIT_L(0); PG8_MMA(0, 0, At, B0); PG8_BAR; PG8_SCHED;
;             PG8_LDB(B1, 1, 1); PG8_STAGE(PG8_SB(1, 0), b3, voffB);
;             PG8_BAR; PG8_WAIT_L(0); PG8_MMA(0, 1, At, B1); PG8_BAR;
;             PG8_LDA(At, 1, 1); PG8_STAGE(PG8_SA(1, 0), a3, voffA);
;             PG8_BAR; PG8_WAIT_L(0); PG8_MMA(1, 0, At, B0); PG8_BAR; PG8_SCHED;
	v_mfma_f32_16x16x32_bf16 v[56:59], v[228:231], v[172:175], v[56:59]
	v_mfma_f32_16x16x32_bf16 v[48:51], v[236:239], v[172:175], v[48:51]
	v_mfma_f32_16x16x32_bf16 v[40:43], v[228:231], v[204:207], v[40:43]
	v_mfma_f32_16x16x32_bf16 v[32:35], v[236:239], v[204:207], v[32:35]
	v_mfma_f32_16x16x32_bf16 v[24:27], v[228:231], v[212:215], v[24:27]
	v_mfma_f32_16x16x32_bf16 v[16:19], v[236:239], v[212:215], v[16:19]
	v_mfma_f32_16x16x32_bf16 v[8:11], v[228:231], v[220:223], v[8:11]
	v_mfma_f32_16x16x32_bf16 v[0:3], v[236:239], v[220:223], v[0:3]
	v_mfma_f32_16x16x32_bf16 v[56:59], v[232:235], v[200:203], v[56:59]
	v_mfma_f32_16x16x32_bf16 v[48:51], v[240:243], v[200:203], v[48:51]
	v_mfma_f32_16x16x32_bf16 v[40:43], v[232:235], v[208:211], v[40:43]
	v_mfma_f32_16x16x32_bf16 v[32:35], v[240:243], v[208:211], v[32:35]
	v_mfma_f32_16x16x32_bf16 v[24:27], v[232:235], v[216:219], v[24:27]
	v_mfma_f32_16x16x32_bf16 v[16:19], v[240:243], v[216:219], v[16:19]
	v_mfma_f32_16x16x32_bf16 v[8:11], v[232:235], v[224:227], v[8:11]
	v_mfma_f32_16x16x32_bf16 v[0:3], v[240:243], v[224:227], v[0:3]
	s_barrier
	s_add_i32 s45, 0, 0x18000
	ds_read_b128 v[144:147], v129 offset:32768
	ds_read_b128 v[160:163], v129 offset:33792
	ds_read_b128 v[164:167], v129 offset:34816
	ds_read_b128 v[168:171], v129 offset:35840
	s_add_u32 s22, s22, 0x80000
	s_addc_u32 s23, s23, 0
	s_mov_b32 m0, s33
	ds_read_b128 v[172:175], v143 offset:32768
	ds_read_b128 v[200:203], v143 offset:33792
	ds_read_b128 v[204:207], v143 offset:34816
	ds_read_b128 v[208:211], v143 offset:35840
	ds_read_b128 v[212:215], v143 offset:36864
	ds_read_b128 v[216:219], v143 offset:37888
	ds_read_b128 v[220:223], v143 offset:38912
	ds_read_b128 v[224:227], v143 offset:39936
	global_load_lds_dwordx4 v132, s[22:23]
	s_mov_b32 m0, s34
	s_nop 0
	global_load_lds_dwordx4 v130, s[22:23]
	s_waitcnt lgkmcnt(8)
	s_barrier
	s_waitcnt lgkmcnt(0)
	v_mfma_f32_16x16x32_bf16 v[124:127], v[144:147], v[172:175], v[124:127]
	v_mfma_f32_16x16x32_bf16 v[116:119], v[164:167], v[172:175], v[116:119]
	v_mfma_f32_16x16x32_bf16 v[108:111], v[144:147], v[204:207], v[108:111]
	v_mfma_f32_16x16x32_bf16 v[100:103], v[164:167], v[204:207], v[100:103]
	v_mfma_f32_16x16x32_bf16 v[92:95], v[144:147], v[212:215], v[92:95]
	v_mfma_f32_16x16x32_bf16 v[84:87], v[164:167], v[212:215], v[84:87]
	v_mfma_f32_16x16x32_bf16 v[76:79], v[144:147], v[220:223], v[76:79]
	v_mfma_f32_16x16x32_bf16 v[68:71], v[164:167], v[220:223], v[68:71]
	v_mfma_f32_16x16x32_bf16 v[124:127], v[160:163], v[200:203], v[124:127]
	v_mfma_f32_16x16x32_bf16 v[116:119], v[168:171], v[200:203], v[116:119]
	v_mfma_f32_16x16x32_bf16 v[108:111], v[160:163], v[208:211], v[108:111]
	v_mfma_f32_16x16x32_bf16 v[100:103], v[168:171], v[208:211], v[100:103]
	v_mfma_f32_16x16x32_bf16 v[92:95], v[160:163], v[216:219], v[92:95]
	v_mfma_f32_16x16x32_bf16 v[84:87], v[168:171], v[216:219], v[84:87]
	v_mfma_f32_16x16x32_bf16 v[76:79], v[160:163], v[224:227], v[76:79]
	v_mfma_f32_16x16x32_bf16 v[68:71], v[168:171], v[224:227], v[68:71]
	s_barrier
	s_add_i32 s22, 0, 0x1c000
	s_add_i32 s23, s45, s29
	s_mov_b32 m0, s23
	ds_read_b128 v[228:231], v129 offset:49152
	ds_read_b128 v[232:235], v129 offset:50176
	ds_read_b128 v[236:239], v129 offset:51200
	ds_read_b128 v[240:243], v129 offset:52224
	global_load_lds_dwordx4 v148, s[84:85]
	s_add_i32 m0, s23, 0x2000
	s_nop 0
	global_load_lds_dwordx4 v128, s[84:85]
	s_barrier
	s_waitcnt lgkmcnt(0)
	v_mfma_f32_16x16x32_bf16 v[120:123], v[228:231], v[172:175], v[120:123]
	v_mfma_f32_16x16x32_bf16 v[112:115], v[236:239], v[172:175], v[112:115]
	v_mfma_f32_16x16x32_bf16 v[104:107], v[228:231], v[204:207], v[104:107]
	v_mfma_f32_16x16x32_bf16 v[96:99], v[236:239], v[204:207], v[96:99]
	v_mfma_f32_16x16x32_bf16 v[88:91], v[228:231], v[212:215], v[88:91]
	v_mfma_f32_16x16x32_bf16 v[80:83], v[236:239], v[212:215], v[80:83]
	v_mfma_f32_16x16x32_bf16 v[72:75], v[228:231], v[220:223], v[72:75]
	v_mfma_f32_16x16x32_bf16 v[64:67], v[236:239], v[220:223], v[64:67]
	v_mfma_f32_16x16x32_bf16 v[120:123], v[232:235], v[200:203], v[120:123]
	v_mfma_f32_16x16x32_bf16 v[112:115], v[240:243], v[200:203], v[112:115]
	v_mfma_f32_16x16x32_bf16 v[104:107], v[232:235], v[208:211], v[104:107]
	v_mfma_f32_16x16x32_bf16 v[96:99], v[240:243], v[208:211], v[96:99]
	v_mfma_f32_16x16x32_bf16 v[88:91], v[232:235], v[216:219], v[88:91]
	v_mfma_f32_16x16x32_bf16 v[80:83], v[240:243], v[216:219], v[80:83]
	v_mfma_f32_16x16x32_bf16 v[72:75], v[232:235], v[224:227], v[72:75]
	v_mfma_f32_16x16x32_bf16 v[64:67], v[240:243], v[224:227], v[64:67]
	s_barrier
	s_mov_b32 m0, s35
	ds_read_b128 v[172:175], v143 offset:49152
	ds_read_b128 v[200:203], v143 offset:50176
	ds_read_b128 v[204:207], v143 offset:51200
	ds_read_b128 v[208:211], v143 offset:52224
	ds_read_b128 v[212:215], v143 offset:53248
	ds_read_b128 v[216:219], v143 offset:54272
	ds_read_b128 v[220:223], v143 offset:55296
	ds_read_b128 v[224:227], v143 offset:56320
	global_load_lds_dwordx4 v132, s[86:87]
	s_mov_b32 m0, s36
	s_nop 0
	global_load_lds_dwordx4 v130, s[86:87]
	s_barrier
	s_waitcnt lgkmcnt(0)
	v_mfma_f32_16x16x32_bf16 v[60:63], v[144:147], v[172:175], v[60:63]
	v_mfma_f32_16x16x32_bf16 v[52:55], v[164:167], v[172:175], v[52:55]
	v_mfma_f32_16x16x32_bf16 v[44:47], v[144:147], v[204:207], v[44:47]
	v_mfma_f32_16x16x32_bf16 v[36:39], v[164:167], v[204:207], v[36:39]
	v_mfma_f32_16x16x32_bf16 v[28:31], v[144:147], v[212:215], v[28:31]
	v_mfma_f32_16x16x32_bf16 v[20:23], v[164:167], v[212:215], v[20:23]
	v_mfma_f32_16x16x32_bf16 v[12:15], v[144:147], v[220:223], v[12:15]
	v_mfma_f32_16x16x32_bf16 v[4:7], v[164:167], v[220:223], v[4:7]
	v_mfma_f32_16x16x32_bf16 v[60:63], v[160:163], v[200:203], v[60:63]
	v_mfma_f32_16x16x32_bf16 v[52:55], v[168:171], v[200:203], v[52:55]
	v_mfma_f32_16x16x32_bf16 v[44:47], v[160:163], v[208:211], v[44:47]
	v_mfma_f32_16x16x32_bf16 v[36:39], v[168:171], v[208:211], v[36:39]
	v_mfma_f32_16x16x32_bf16 v[28:31], v[160:163], v[216:219], v[28:31]
	v_mfma_f32_16x16x32_bf16 v[20:23], v[168:171], v[216:219], v[20:23]
	v_mfma_f32_16x16x32_bf16 v[12:15], v[160:163], v[224:227], v[12:15]
	v_mfma_f32_16x16x32_bf16 v[4:7], v[168:171], v[224:227], v[4:7]
	s_barrier
; __device__ __forceinline__ unsigned cvt_pk_bf16(float lo, float hi) { unsigned r; asm("v_cvt_pk_bf16_f32 %0, %1, %2" : "=v"(r) : "v"(lo), "v"(hi)); return r; }
; #define PG8_STAGE(bufoff, gbase, voff) do { _Pragma("unroll") for (int _i = 0; _i < 2; ++_i) \
;         __builtin_amdgcn_global_load_lds((const unsigned*)((const char*)(gbase) + (voff)[_i]), (LAS unsigned*)(lds + (bufoff) + ldsw + _i * 8192), 16, 0, 0); } while (0)
; #define PG8_MMA(ai, bj, At, Bt) do { __builtin_amdgcn_s_setprio(1); _Pragma("unroll") for (int m = 0; m < 4; ++m) _Pragma("unroll") for (int n = 0; n < 2; ++n) _Pragma("unroll") for (int k = 0; k < 2; ++k) \
;         acc[ai][bj][m][n] = __builtin_amdgcn_mfma_f32_16x16x32_bf16(Bt[n][k], At[m][k], acc[ai][bj][m][n], 0, 0, 0); __builtin_amdgcn_s_setprio(0); } while (0)
; #define PG8_WAIT_V(n) asm volatile("s_waitcnt vmcnt(" #n ")" ::: "memory")
; #define PG8_BAR __builtin_amdgcn_s_barrier()
;     __device__ __forceinline__ void operator()(const f32x4 (&acc)[2][2][4][2], const Unit& u, int wr, int wc, int fr, int fq) const {
;         const int row0 = u.pm * BM + wr * 64 + fr, col0 = u.pn * HALF + wc * 32 + 8 * fq;
; #pragma unroll
;         for (int ai = 0; ai < 2; ++ai)
; #pragma unroll
;             for (int m = 0; m < 4; ++m) { bf16_t* rowp = O + (size_t)(row0 + ai * HALF + m * 16) * ldc + col0;
;                 float h[8];
; #pragma unroll
;                 for (int n = 0; n < 2; ++n)
; #pragma unroll
;                     for (int j = 0; j < 4; ++j) { const float g = acc[ai][0][m][n][j], up = acc[ai][1][m][n][j];
;                         const float e = __builtin_amdgcn_exp2f(-1.4426950408889634f * g);
;                         h[n * 4 + j] = g * __builtin_amdgcn_rcpf(1.0f + e) * up; }
;                 u32x4 w; w.x = cvt_pk_bf16(h[0], h[1]); w.y = cvt_pk_bf16(h[2], h[3]); w.z = cvt_pk_bf16(h[4], h[5]); w.w = cvt_pk_bf16(h[6], h[7]);
;                 *(u32x4*)rowp = w; }
; template <class Epi, class Sched>
; __device__ __forceinline__ void gemm_phase(LAS unsigned char* lds, const Gemm g, const Sched& S, const Epi& E) {
;     ...
;             PG8_STAGE(PG8_SB(1, 1), b3 + hstep, voffB);
;             PG8_WAIT_V(6); PG8_BAR; PG8_MMA(1, 1, At, B1); PG8_BAR;
	s_add_u32 s20, s20, 0x80080
	s_addc_u32 s21, s21, 0
	s_add_i32 s22, s22, s29
	s_mov_b32 m0, s22
	s_nop 0
	global_load_lds_dwordx4 v148, s[20:21]
	s_add_i32 m0, s22, 0x2000
	s_nop 0
	global_load_lds_dwordx4 v128, s[20:21]
	s_add_i32 s44, s44, 2
	s_add_u32 s16, s16, 0x100
	s_addc_u32 s17, s17, 0
	s_add_u32 s42, s42, 0x100
	s_addc_u32 s43, s43, 0
	s_cmp_gt_u32 s44, 29
	s_waitcnt vmcnt(6)
	s_barrier
	v_mfma_f32_16x16x32_bf16 v[56:59], v[228:231], v[172:175], v[56:59]
	v_mfma_f32_16x16x32_bf16 v[48:51], v[236:239], v[172:175], v[48:51]
	v_mfma_f32_16x16x32_bf16 v[40:43], v[228:231], v[204:207], v[40:43]
	v_mfma_f32_16x16x32_bf16 v[32:35], v[236:239], v[204:207], v[32:35]
	v_mfma_f32_16x16x32_bf16 v[24:27], v[228:231], v[212:215], v[24:27]
	v_mfma_f32_16x16x32_bf16 v[16:19], v[236:239], v[212:215], v[16:19]
	v_mfma_f32_16x16x32_bf16 v[8:11], v[228:231], v[220:223], v[8:11]
	v_mfma_f32_16x16x32_bf16 v[0:3], v[236:239], v[220:223], v[0:3]
	v_mfma_f32_16x16x32_bf16 v[56:59], v[232:235], v[200:203], v[56:59]
	v_mfma_f32_16x16x32_bf16 v[48:51], v[240:243], v[200:203], v[48:51]
	v_mfma_f32_16x16x32_bf16 v[40:43], v[232:235], v[208:211], v[40:43]
	v_mfma_f32_16x16x32_bf16 v[32:35], v[240:243], v[208:211], v[32:35]
	v_mfma_f32_16x16x32_bf16 v[24:27], v[232:235], v[216:219], v[24:27]
	v_mfma_f32_16x16x32_bf16 v[16:19], v[240:243], v[216:219], v[16:19]
	v_mfma_f32_16x16x32_bf16 v[8:11], v[232:235], v[224:227], v[8:11]
	v_mfma_f32_16x16x32_bf16 v[0:3], v[240:243], v[224:227], v[0:3]
	s_barrier
	s_cbranch_scc0 .LBB0_213
	v_mul_f32_e32 v145, 0xbfb8aa3b, v124
	v_exp_f32_e32 v145, v145
	v_lshl_or_b32 v146, s38, 7, v142
	v_lshl_add_u32 v144, s39, 8, v140
	v_ashrrev_i32_e32 v147, 31, v146
	v_add_f32_e32 v145, 1.0, v145
	v_rcp_f32_e32 v145, v145
	v_mov_b64_e32 v[138:139], s[4:5]
	s_movk_i32 s7, 0x2c00
	v_mad_i64_i32 v[160:161], s[16:17], v144, s7, v[138:139]
	v_mul_f32_e32 v124, v124, v145
	v_mul_f32_e32 v120, v120, v124
	v_mul_f32_e32 v124, 0xbfb8aa3b, v125
	v_exp_f32_e32 v124, v124
	s_and_b64 vcc, exec, s[0:1]
	s_mov_b32 s38, s6
	s_mov_b32 s39, s10
	v_add_f32_e32 v124, 1.0, v124
	v_rcp_f32_e32 v124, v124
	s_mov_b64 s[20:21], s[14:15]
	v_mul_f32_e32 v124, v125, v124
	v_mul_f32_e32 v121, v121, v124
	v_mul_f32_e32 v124, 0xbfb8aa3b, v126
	v_exp_f32_e32 v124, v124
	s_nop 0
	v_add_f32_e32 v124, 1.0, v124
	v_rcp_f32_e32 v124, v124
	s_nop 0
	v_mul_f32_e32 v124, v126, v124
	v_mul_f32_e32 v122, v122, v124
	v_mul_f32_e32 v124, 0xbfb8aa3b, v127
	v_exp_f32_e32 v124, v124
	s_nop 0
	v_add_f32_e32 v124, 1.0, v124
	v_rcp_f32_e32 v124, v124
	s_nop 0
	v_mul_f32_e32 v124, v127, v124
	v_mul_f32_e32 v123, v123, v124
	v_mul_f32_e32 v124, 0xbfb8aa3b, v116
	v_exp_f32_e32 v124, v124
	s_nop 0
	v_add_f32_e32 v124, 1.0, v124
	v_rcp_f32_e32 v124, v124
	s_nop 0
	v_mul_f32_e32 v116, v116, v124
	v_mul_f32_e32 v116, v112, v116
	v_mul_f32_e32 v112, 0xbfb8aa3b, v117
	v_exp_f32_e32 v112, v112
	s_nop 0
	v_add_f32_e32 v112, 1.0, v112
	v_rcp_f32_e32 v112, v112
	s_nop 0
	v_mul_f32_e32 v112, v117, v112
	v_mul_f32_e32 v117, v113, v112
	v_mul_f32_e32 v112, 0xbfb8aa3b, v118
	v_exp_f32_e32 v112, v112
	v_cvt_pk_bf16_f32 v116, v116, v117
	s_nop 0
	v_add_f32_e32 v112, 1.0, v112
	v_rcp_f32_e32 v112, v112
	s_nop 0
	v_mul_f32_e32 v112, v118, v112
	v_mul_f32_e32 v124, v114, v112
	v_mul_f32_e32 v112, 0xbfb8aa3b, v119
	v_exp_f32_e32 v112, v112
	v_cvt_pk_bf16_f32 v114, v120, v121
	s_nop 0
	v_add_f32_e32 v112, 1.0, v112
	v_rcp_f32_e32 v112, v112
	s_nop 0
	v_mul_f32_e32 v112, v119, v112
	v_mul_f32_e32 v125, v115, v112
	v_lshlrev_b64 v[112:113], 1, v[146:147]
	v_lshl_add_u64 v[118:119], v[160:161], 0, v[112:113]
	v_cvt_pk_bf16_f32 v115, v122, v123
	v_cvt_pk_bf16_f32 v117, v124, v125
	global_store_dwordx4 v[118:119], v[114:117], off
	s_nop 1
	v_mul_f32_e32 v116, 0xbfb8aa3b, v108
	v_exp_f32_e32 v116, v116
	v_or_b32_e32 v114, 16, v144
	v_mad_i64_i32 v[114:115], s[16:17], v114, s7, v[138:139]
	v_add_f32_e32 v116, 1.0, v116
	v_rcp_f32_e32 v116, v116
	s_nop 0
	v_mul_f32_e32 v108, v108, v116
	v_mul_f32_e32 v104, v104, v108
	v_mul_f32_e32 v108, 0xbfb8aa3b, v109
	v_exp_f32_e32 v108, v108
	s_nop 0
	v_add_f32_e32 v108, 1.0, v108
	v_rcp_f32_e32 v108, v108
	s_nop 0
	v_mul_f32_e32 v108, v109, v108
	v_mul_f32_e32 v105, v105, v108
	v_mul_f32_e32 v108, 0xbfb8aa3b, v110
	v_exp_f32_e32 v108, v108
	s_nop 0
	v_add_f32_e32 v108, 1.0, v108
	v_rcp_f32_e32 v108, v108
	s_nop 0
	v_mul_f32_e32 v108, v110, v108
	v_mul_f32_e32 v106, v106, v108
	v_mul_f32_e32 v108, 0xbfb8aa3b, v111
	v_exp_f32_e32 v108, v108
	s_nop 0
	v_add_f32_e32 v108, 1.0, v108
	v_rcp_f32_e32 v108, v108
	s_nop 0
	v_mul_f32_e32 v108, v111, v108
	v_mul_f32_e32 v107, v107, v108
	v_mul_f32_e32 v108, 0xbfb8aa3b, v100
	v_exp_f32_e32 v108, v108
	s_nop 0
	v_add_f32_e32 v108, 1.0, v108
	v_rcp_f32_e32 v108, v108
	s_nop 0
	v_mul_f32_e32 v100, v100, v108
	v_mul_f32_e32 v108, v96, v100
	v_mul_f32_e32 v96, 0xbfb8aa3b, v101
	v_exp_f32_e32 v96, v96
	s_nop 0
	v_add_f32_e32 v96, 1.0, v96
	v_rcp_f32_e32 v96, v96
	s_nop 0
	v_mul_f32_e32 v96, v101, v96
	v_mul_f32_e32 v109, v97, v96
	v_mul_f32_e32 v96, 0xbfb8aa3b, v102
	v_exp_f32_e32 v96, v96
	v_lshl_add_u64 v[100:101], v[114:115], 0, v[112:113]
	v_cvt_pk_bf16_f32 v97, v106, v107
	v_add_f32_e32 v96, 1.0, v96
	v_rcp_f32_e32 v96, v96
	s_nop 0
	v_mul_f32_e32 v96, v102, v96
	v_mul_f32_e32 v102, v98, v96
	v_mul_f32_e32 v96, 0xbfb8aa3b, v103
	v_exp_f32_e32 v96, v96
	v_cvt_pk_bf16_f32 v98, v108, v109
	s_nop 0
	v_add_f32_e32 v96, 1.0, v96
	v_rcp_f32_e32 v96, v96
	s_nop 0
	v_mul_f32_e32 v96, v103, v96
	v_mul_f32_e32 v99, v99, v96
	v_cvt_pk_bf16_f32 v96, v104, v105
	v_cvt_pk_bf16_f32 v99, v102, v99
	global_store_dwordx4 v[100:101], v[96:99], off
	s_nop 1
; __device__ __forceinline__ unsigned cvt_pk_bf16(float lo, float hi) { unsigned r; asm("v_cvt_pk_bf16_f32 %0, %1, %2" : "=v"(r) : "v"(lo), "v"(hi)); return r; }
;     __device__ __forceinline__ void operator()(const f32x4 (&acc)[2][2][4][2], const Unit& u, int wr, int wc, int fr, int fq) const {
;         const int row0 = u.pm * BM + wr * 64 + fr, col0 = u.pn * HALF + wc * 32 + 8 * fq;
; #pragma unroll
;         for (int ai = 0; ai < 2; ++ai)
; #pragma unroll
;             for (int m = 0; m < 4; ++m) { bf16_t* rowp = O + (size_t)(row0 + ai * HALF + m * 16) * ldc + col0;
;                 float h[8];
; #pragma unroll
;                 for (int n = 0; n < 2; ++n)
; #pragma unroll
;                     for (int j = 0; j < 4; ++j) { const float g = acc[ai][0][m][n][j], up = acc[ai][1][m][n][j];
;                         const float e = __builtin_amdgcn_exp2f(-1.4426950408889634f * g);
;                         h[n * 4 + j] = g * __builtin_amdgcn_rcpf(1.0f + e) * up; }
;                 u32x4 w; w.x = cvt_pk_bf16(h[0], h[1]); w.y = cvt_pk_bf16(h[2], h[3]); w.z = cvt_pk_bf16(h[4], h[5]); w.w = cvt_pk_bf16(h[6], h[7]);
;                 *(u32x4*)rowp = w; }
	v_mul_f32_e32 v98, 0xbfb8aa3b, v92
	v_exp_f32_e32 v98, v98
	v_or_b32_e32 v96, 32, v144
	v_mad_i64_i32 v[96:97], s[16:17], v96, s7, v[138:139]
	v_add_f32_e32 v98, 1.0, v98
	v_rcp_f32_e32 v98, v98
	s_nop 0
	v_mul_f32_e32 v92, v92, v98
	v_mul_f32_e32 v88, v88, v92
	v_mul_f32_e32 v92, 0xbfb8aa3b, v93
	v_exp_f32_e32 v92, v92
	s_nop 0
	v_add_f32_e32 v92, 1.0, v92
	v_rcp_f32_e32 v92, v92
	s_nop 0
	v_mul_f32_e32 v92, v93, v92
	v_mul_f32_e32 v89, v89, v92
	v_mul_f32_e32 v92, 0xbfb8aa3b, v94
	v_exp_f32_e32 v92, v92
	s_nop 0
	v_add_f32_e32 v92, 1.0, v92
	v_rcp_f32_e32 v92, v92
	s_nop 0
	v_mul_f32_e32 v92, v94, v92
	v_mul_f32_e32 v90, v90, v92
	v_mul_f32_e32 v92, 0xbfb8aa3b, v95
	v_exp_f32_e32 v92, v92
	s_nop 0
	v_add_f32_e32 v92, 1.0, v92
	v_rcp_f32_e32 v92, v92
	s_nop 0
	v_mul_f32_e32 v92, v95, v92
	v_mul_f32_e32 v91, v91, v92
	v_mul_f32_e32 v92, 0xbfb8aa3b, v84
	v_exp_f32_e32 v92, v92
	s_nop 0
	v_add_f32_e32 v92, 1.0, v92
	v_rcp_f32_e32 v92, v92
	s_nop 0
	v_mul_f32_e32 v84, v84, v92
	v_mul_f32_e32 v92, v80, v84
	v_mul_f32_e32 v80, 0xbfb8aa3b, v85
	v_exp_f32_e32 v80, v80
	s_nop 0
	v_add_f32_e32 v80, 1.0, v80
	v_rcp_f32_e32 v80, v80
	s_nop 0
	v_mul_f32_e32 v80, v85, v80
	v_mul_f32_e32 v93, v81, v80
	v_mul_f32_e32 v80, 0xbfb8aa3b, v86
	v_exp_f32_e32 v80, v80
	v_lshl_add_u64 v[84:85], v[96:97], 0, v[112:113]
	v_cvt_pk_bf16_f32 v81, v90, v91
	v_add_f32_e32 v80, 1.0, v80
	v_rcp_f32_e32 v80, v80
	s_nop 0
	v_mul_f32_e32 v80, v86, v80
	v_mul_f32_e32 v86, v82, v80
	v_mul_f32_e32 v80, 0xbfb8aa3b, v87
	v_exp_f32_e32 v80, v80
	v_cvt_pk_bf16_f32 v82, v92, v93
	s_nop 0
	v_add_f32_e32 v80, 1.0, v80
	v_rcp_f32_e32 v80, v80
	s_nop 0
	v_mul_f32_e32 v80, v87, v80
	v_mul_f32_e32 v83, v83, v80
	v_cvt_pk_bf16_f32 v80, v88, v89
	v_cvt_pk_bf16_f32 v83, v86, v83
	global_store_dwordx4 v[84:85], v[80:83], off
	s_nop 1
	v_mul_f32_e32 v82, 0xbfb8aa3b, v76
	v_exp_f32_e32 v82, v82
	v_or_b32_e32 v80, 48, v144
	v_mad_i64_i32 v[80:81], s[16:17], v80, s7, v[138:139]
	v_add_f32_e32 v82, 1.0, v82
	v_rcp_f32_e32 v82, v82
	s_nop 0
	v_mul_f32_e32 v76, v76, v82
	v_mul_f32_e32 v72, v72, v76
	v_mul_f32_e32 v76, 0xbfb8aa3b, v77
	v_exp_f32_e32 v76, v76
	s_nop 0
	v_add_f32_e32 v76, 1.0, v76
	v_rcp_f32_e32 v76, v76
	s_nop 0
	v_mul_f32_e32 v76, v77, v76
	v_mul_f32_e32 v73, v73, v76
	v_mul_f32_e32 v76, 0xbfb8aa3b, v78
	v_exp_f32_e32 v76, v76
	s_nop 0
	v_add_f32_e32 v76, 1.0, v76
	v_rcp_f32_e32 v76, v76
	s_nop 0
	v_mul_f32_e32 v76, v78, v76
	v_mul_f32_e32 v74, v74, v76
	v_mul_f32_e32 v76, 0xbfb8aa3b, v79
	v_exp_f32_e32 v76, v76
	s_nop 0
	v_add_f32_e32 v76, 1.0, v76
	v_rcp_f32_e32 v76, v76
	s_nop 0
	v_mul_f32_e32 v76, v79, v76
	v_mul_f32_e32 v75, v75, v76
	v_mul_f32_e32 v76, 0xbfb8aa3b, v68
	v_exp_f32_e32 v76, v76
	s_nop 0
	v_add_f32_e32 v76, 1.0, v76
	v_rcp_f32_e32 v76, v76
	s_nop 0
	v_mul_f32_e32 v68, v68, v76
	v_mul_f32_e32 v76, v64, v68
	v_mul_f32_e32 v64, 0xbfb8aa3b, v69
	v_exp_f32_e32 v64, v64
	s_nop 0
	v_add_f32_e32 v64, 1.0, v64
	v_rcp_f32_e32 v64, v64
	s_nop 0
	v_mul_f32_e32 v64, v69, v64
	v_mul_f32_e32 v77, v65, v64
	v_mul_f32_e32 v64, 0xbfb8aa3b, v70
	v_exp_f32_e32 v64, v64
	v_lshl_add_u64 v[68:69], v[80:81], 0, v[112:113]
	v_cvt_pk_bf16_f32 v65, v74, v75
	v_add_f32_e32 v64, 1.0, v64
	v_rcp_f32_e32 v64, v64
	s_nop 0
	v_mul_f32_e32 v64, v70, v64
	v_mul_f32_e32 v70, v66, v64
	v_mul_f32_e32 v64, 0xbfb8aa3b, v71
	v_exp_f32_e32 v64, v64
	v_cvt_pk_bf16_f32 v66, v76, v77
	s_nop 0
	v_add_f32_e32 v64, 1.0, v64
	v_rcp_f32_e32 v64, v64
	s_nop 0
	v_mul_f32_e32 v64, v71, v64
	v_mul_f32_e32 v67, v67, v64
	v_cvt_pk_bf16_f32 v64, v72, v73
	v_cvt_pk_bf16_f32 v67, v70, v67
	global_store_dwordx4 v[68:69], v[64:67], off
	s_nop 1
	v_mul_f32_e32 v66, 0xbfb8aa3b, v60
	v_exp_f32_e32 v66, v66
	v_add_u32_e32 v64, 0x80, v144
	v_mad_i64_i32 v[64:65], s[16:17], v64, s7, v[138:139]
	v_add_f32_e32 v66, 1.0, v66
	v_rcp_f32_e32 v66, v66
	s_nop 0
	v_mul_f32_e32 v60, v60, v66
	v_mul_f32_e32 v56, v56, v60
	v_mul_f32_e32 v60, 0xbfb8aa3b, v61
	v_exp_f32_e32 v60, v60
	s_nop 0
	v_add_f32_e32 v60, 1.0, v60
	v_rcp_f32_e32 v60, v60
	s_nop 0
	v_mul_f32_e32 v60, v61, v60
	v_mul_f32_e32 v57, v57, v60
	v_mul_f32_e32 v60, 0xbfb8aa3b, v62
	v_exp_f32_e32 v60, v60
	s_nop 0
	v_add_f32_e32 v60, 1.0, v60
	v_rcp_f32_e32 v60, v60
	s_nop 0
	v_mul_f32_e32 v60, v62, v60
	v_mul_f32_e32 v58, v58, v60
	v_mul_f32_e32 v60, 0xbfb8aa3b, v63
	v_exp_f32_e32 v60, v60
	s_nop 0
	v_add_f32_e32 v60, 1.0, v60
	v_rcp_f32_e32 v60, v60
	s_nop 0
	v_mul_f32_e32 v60, v63, v60
	v_mul_f32_e32 v59, v59, v60
	v_mul_f32_e32 v60, 0xbfb8aa3b, v52
	v_exp_f32_e32 v60, v60
	s_nop 0
	v_add_f32_e32 v60, 1.0, v60
	v_rcp_f32_e32 v60, v60
	s_nop 0
	v_mul_f32_e32 v52, v52, v60
	v_mul_f32_e32 v60, v48, v52
	v_mul_f32_e32 v48, 0xbfb8aa3b, v53
	v_exp_f32_e32 v48, v48
	s_nop 0
	v_add_f32_e32 v48, 1.0, v48
	v_rcp_f32_e32 v48, v48
	s_nop 0
	v_mul_f32_e32 v48, v53, v48
	v_mul_f32_e32 v61, v49, v48
	v_mul_f32_e32 v48, 0xbfb8aa3b, v54
	v_exp_f32_e32 v48, v48
	v_lshl_add_u64 v[52:53], v[64:65], 0, v[112:113]
	v_cvt_pk_bf16_f32 v49, v58, v59
	v_add_f32_e32 v48, 1.0, v48
	v_rcp_f32_e32 v48, v48
	s_nop 0
	v_mul_f32_e32 v48, v54, v48
	v_mul_f32_e32 v54, v50, v48
	v_mul_f32_e32 v48, 0xbfb8aa3b, v55
	v_exp_f32_e32 v48, v48
	v_cvt_pk_bf16_f32 v50, v60, v61
	s_nop 0
	v_add_f32_e32 v48, 1.0, v48
	v_rcp_f32_e32 v48, v48
	s_nop 0
	v_mul_f32_e32 v48, v55, v48
	v_mul_f32_e32 v51, v51, v48
	v_cvt_pk_bf16_f32 v48, v56, v57
	v_cvt_pk_bf16_f32 v51, v54, v51
	global_store_dwordx4 v[52:53], v[48:51], off
	s_nop 1
	v_mul_f32_e32 v50, 0xbfb8aa3b, v44
; __device__ __forceinline__ unsigned cvt_pk_bf16(float lo, float hi) { unsigned r; asm("v_cvt_pk_bf16_f32 %0, %1, %2" : "=v"(r) : "v"(lo), "v"(hi)); return r; }
;     __device__ __forceinline__ void operator()(const f32x4 (&acc)[2][2][4][2], const Unit& u, int wr, int wc, int fr, int fq) const {
;         const int row0 = u.pm * BM + wr * 64 + fr, col0 = u.pn * HALF + wc * 32 + 8 * fq;
; #pragma unroll
;         for (int ai = 0; ai < 2; ++ai)
; #pragma unroll
;             for (int m = 0; m < 4; ++m) { bf16_t* rowp = O + (size_t)(row0 + ai * HALF + m * 16) * ldc + col0;
;                 float h[8];
; #pragma unroll
;                 for (int n = 0; n < 2; ++n)
; #pragma unroll
;                     for (int j = 0; j < 4; ++j) { const float g = acc[ai][0][m][n][j], up = acc[ai][1][m][n][j];
;                         const float e = __builtin_amdgcn_exp2f(-1.4426950408889634f * g);
;                         h[n * 4 + j] = g * __builtin_amdgcn_rcpf(1.0f + e) * up; }
;                 u32x4 w; w.x = cvt_pk_bf16(h[0], h[1]); w.y = cvt_pk_bf16(h[2], h[3]); w.z = cvt_pk_bf16(h[4], h[5]); w.w = cvt_pk_bf16(h[6], h[7]);
;                 *(u32x4*)rowp = w; }
	v_exp_f32_e32 v50, v50
	v_add_u32_e32 v48, 0x90, v144
	v_mad_i64_i32 v[48:49], s[16:17], v48, s7, v[138:139]
	v_add_f32_e32 v50, 1.0, v50
	v_rcp_f32_e32 v50, v50
	s_nop 0
	v_mul_f32_e32 v44, v44, v50
	v_mul_f32_e32 v40, v40, v44
	v_mul_f32_e32 v44, 0xbfb8aa3b, v45
	v_exp_f32_e32 v44, v44
	s_nop 0
	v_add_f32_e32 v44, 1.0, v44
	v_rcp_f32_e32 v44, v44
	s_nop 0
	v_mul_f32_e32 v44, v45, v44
	v_mul_f32_e32 v41, v41, v44
	v_mul_f32_e32 v44, 0xbfb8aa3b, v46
	v_exp_f32_e32 v44, v44
	s_nop 0
	v_add_f32_e32 v44, 1.0, v44
	v_rcp_f32_e32 v44, v44
	s_nop 0
	v_mul_f32_e32 v44, v46, v44
	v_mul_f32_e32 v42, v42, v44
	v_mul_f32_e32 v44, 0xbfb8aa3b, v47
	v_exp_f32_e32 v44, v44
	s_nop 0
	v_add_f32_e32 v44, 1.0, v44
	v_rcp_f32_e32 v44, v44
	s_nop 0
	v_mul_f32_e32 v44, v47, v44
	v_mul_f32_e32 v43, v43, v44
	v_mul_f32_e32 v44, 0xbfb8aa3b, v36
	v_exp_f32_e32 v44, v44
	s_nop 0
	v_add_f32_e32 v44, 1.0, v44
	v_rcp_f32_e32 v44, v44
	s_nop 0
	v_mul_f32_e32 v36, v36, v44
	v_mul_f32_e32 v44, v32, v36
	v_mul_f32_e32 v32, 0xbfb8aa3b, v37
	v_exp_f32_e32 v32, v32
	s_nop 0
	v_add_f32_e32 v32, 1.0, v32
	v_rcp_f32_e32 v32, v32
	s_nop 0
	v_mul_f32_e32 v32, v37, v32
	v_mul_f32_e32 v45, v33, v32
	v_mul_f32_e32 v32, 0xbfb8aa3b, v38
	v_exp_f32_e32 v32, v32
	v_lshl_add_u64 v[36:37], v[48:49], 0, v[112:113]
	v_cvt_pk_bf16_f32 v33, v42, v43
	v_add_f32_e32 v32, 1.0, v32
	v_rcp_f32_e32 v32, v32
	s_nop 0
	v_mul_f32_e32 v32, v38, v32
	v_mul_f32_e32 v38, v34, v32
	v_mul_f32_e32 v32, 0xbfb8aa3b, v39
	v_exp_f32_e32 v32, v32
	v_cvt_pk_bf16_f32 v34, v44, v45
	s_nop 0
	v_add_f32_e32 v32, 1.0, v32
	v_rcp_f32_e32 v32, v32
	s_nop 0
	v_mul_f32_e32 v32, v39, v32
	v_mul_f32_e32 v35, v35, v32
	v_cvt_pk_bf16_f32 v32, v40, v41
	v_cvt_pk_bf16_f32 v35, v38, v35
	global_store_dwordx4 v[36:37], v[32:35], off
	s_nop 1
	v_mul_f32_e32 v34, 0xbfb8aa3b, v28
	v_exp_f32_e32 v34, v34
	v_add_u32_e32 v32, 0xa0, v144
	v_mad_i64_i32 v[32:33], s[16:17], v32, s7, v[138:139]
	v_add_f32_e32 v34, 1.0, v34
	v_rcp_f32_e32 v34, v34
	s_nop 0
	v_mul_f32_e32 v28, v28, v34
	v_mul_f32_e32 v24, v24, v28
	v_mul_f32_e32 v28, 0xbfb8aa3b, v29
	v_exp_f32_e32 v28, v28
	s_nop 0
	v_add_f32_e32 v28, 1.0, v28
	v_rcp_f32_e32 v28, v28
	s_nop 0
	v_mul_f32_e32 v28, v29, v28
	v_mul_f32_e32 v25, v25, v28
	v_mul_f32_e32 v28, 0xbfb8aa3b, v30
	v_exp_f32_e32 v28, v28
	s_nop 0
	v_add_f32_e32 v28, 1.0, v28
	v_rcp_f32_e32 v28, v28
	s_nop 0
	v_mul_f32_e32 v28, v30, v28
	v_mul_f32_e32 v26, v26, v28
	v_mul_f32_e32 v28, 0xbfb8aa3b, v31
	v_exp_f32_e32 v28, v28
	s_nop 0
	v_add_f32_e32 v28, 1.0, v28
	v_rcp_f32_e32 v28, v28
	s_nop 0
	v_mul_f32_e32 v28, v31, v28
	v_mul_f32_e32 v27, v27, v28
	v_mul_f32_e32 v28, 0xbfb8aa3b, v20
	v_exp_f32_e32 v28, v28
	s_nop 0
	v_add_f32_e32 v28, 1.0, v28
	v_rcp_f32_e32 v28, v28
	s_nop 0
	v_mul_f32_e32 v20, v20, v28
	v_mul_f32_e32 v28, v16, v20
	v_mul_f32_e32 v16, 0xbfb8aa3b, v21
	v_exp_f32_e32 v16, v16
	s_nop 0
	v_add_f32_e32 v16, 1.0, v16
	v_rcp_f32_e32 v16, v16
	s_nop 0
	v_mul_f32_e32 v16, v21, v16
	v_mul_f32_e32 v29, v17, v16
	v_mul_f32_e32 v16, 0xbfb8aa3b, v22
	v_exp_f32_e32 v16, v16
	v_lshl_add_u64 v[20:21], v[32:33], 0, v[112:113]
	v_cvt_pk_bf16_f32 v17, v26, v27
	v_add_f32_e32 v16, 1.0, v16
	v_rcp_f32_e32 v16, v16
	s_nop 0
	v_mul_f32_e32 v16, v22, v16
	v_mul_f32_e32 v22, v18, v16
	v_mul_f32_e32 v16, 0xbfb8aa3b, v23
	v_exp_f32_e32 v16, v16
	v_cvt_pk_bf16_f32 v18, v28, v29
	s_nop 0
	v_add_f32_e32 v16, 1.0, v16
	v_rcp_f32_e32 v16, v16
	s_nop 0
	v_mul_f32_e32 v16, v23, v16
	v_mul_f32_e32 v19, v19, v16
	v_cvt_pk_bf16_f32 v16, v24, v25
	v_cvt_pk_bf16_f32 v19, v22, v19
	global_store_dwordx4 v[20:21], v[16:19], off
	s_nop 1
	v_mul_f32_e32 v18, 0xbfb8aa3b, v12
	v_exp_f32_e32 v18, v18
	v_add_u32_e32 v16, 0xb0, v144
	v_mad_i64_i32 v[16:17], s[16:17], v16, s7, v[138:139]
	v_add_f32_e32 v18, 1.0, v18
	v_rcp_f32_e32 v18, v18
	s_mov_b64 s[16:17], s[12:13]
	v_mul_f32_e32 v12, v12, v18
	v_mul_f32_e32 v8, v8, v12
	v_mul_f32_e32 v12, 0xbfb8aa3b, v13
	v_exp_f32_e32 v12, v12
	s_nop 0
	v_add_f32_e32 v12, 1.0, v12
	v_rcp_f32_e32 v12, v12
	s_nop 0
	v_mul_f32_e32 v12, v13, v12
	v_mul_f32_e32 v9, v9, v12
	v_mul_f32_e32 v12, 0xbfb8aa3b, v14
	v_exp_f32_e32 v12, v12
	s_nop 0
	v_add_f32_e32 v12, 1.0, v12
	v_rcp_f32_e32 v12, v12
	s_nop 0
	v_mul_f32_e32 v12, v14, v12
	v_mul_f32_e32 v10, v10, v12
	v_mul_f32_e32 v12, 0xbfb8aa3b, v15
	v_exp_f32_e32 v12, v12
	s_nop 0
	v_add_f32_e32 v12, 1.0, v12
	v_rcp_f32_e32 v12, v12
	s_nop 0
	v_mul_f32_e32 v12, v15, v12
	v_mul_f32_e32 v11, v11, v12
	v_mul_f32_e32 v12, 0xbfb8aa3b, v4
	v_exp_f32_e32 v12, v12
	s_nop 0
	v_add_f32_e32 v12, 1.0, v12
	v_rcp_f32_e32 v12, v12
	s_nop 0
	v_mul_f32_e32 v4, v4, v12
	v_mul_f32_e32 v12, v0, v4
	v_mul_f32_e32 v0, 0xbfb8aa3b, v5
	v_exp_f32_e32 v0, v0
	s_nop 0
	v_add_f32_e32 v0, 1.0, v0
	v_rcp_f32_e32 v0, v0
	s_nop 0
	v_mul_f32_e32 v0, v5, v0
	v_mul_f32_e32 v13, v1, v0
	v_mul_f32_e32 v0, 0xbfb8aa3b, v6
	v_exp_f32_e32 v0, v0
	v_lshl_add_u64 v[4:5], v[16:17], 0, v[112:113]
	v_cvt_pk_bf16_f32 v1, v10, v11
	v_add_f32_e32 v0, 1.0, v0
	v_rcp_f32_e32 v0, v0
	s_nop 0
	v_mul_f32_e32 v0, v6, v0
	v_mul_f32_e32 v6, v2, v0
	v_mul_f32_e32 v0, 0xbfb8aa3b, v7
	v_exp_f32_e32 v0, v0
	v_cvt_pk_bf16_f32 v2, v12, v13
	s_nop 0
	v_add_f32_e32 v0, 1.0, v0
	v_rcp_f32_e32 v0, v0
	s_nop 0
	v_mul_f32_e32 v0, v7, v0
	v_mul_f32_e32 v3, v3, v0
	v_cvt_pk_bf16_f32 v0, v8, v9
	v_cvt_pk_bf16_f32 v3, v6, v3
	global_store_dwordx4 v[4:5], v[0:3], off
	s_cbranch_vccz .LBB0_210
	s_waitcnt vmcnt(0)
	s_cmpk_gt_u32 s24, 0xff
	s_cbranch_scc1 .LBB0_217
	s_barrier
